# scan: decay scaling deferred to once per 8-token group (state kept divided by the running decay product; pre-scaled kk/b/kd/r rows prepared per group), token loops have no per-token scaling
# speedup vs baseline: 1.0602x; 1.0104x over previous
.LBB0_362:
	s_add_i32 s12, s21, -7
	s_and_b64 s[22:23], s[2:3], exec
	s_cselect_b32 s15, s21, s12
	s_add_i32 s12, s15, -1
	s_max_i32 s12, s12, s14
	s_min_i32 s12, s12, s17
	s_mulk_i32 s12, 0x1800
	v_lshl_add_u64 v[130:131], v[158:159], 0, s[12:13]
	s_max_i32 s12, s15, s14
	s_min_i32 s12, s12, s17
	s_mulk_i32 s12, 0x1800
	v_lshl_add_u64 v[132:133], v[158:159], 0, s[12:13]
	s_add_i32 s12, s15, 1
	s_max_i32 s12, s12, s14
	s_min_i32 s12, s12, s17
	s_mulk_i32 s12, 0x1800
	v_lshl_add_u64 v[134:135], v[158:159], 0, s[12:13]
	s_add_i32 s12, s15, 2
	s_max_i32 s12, s12, s14
	s_min_i32 s12, s12, s17
	s_mulk_i32 s12, 0x1800
	v_lshl_add_u64 v[136:137], v[158:159], 0, s[12:13]
	s_add_i32 s12, s15, 3
	s_max_i32 s12, s12, s14
	s_min_i32 s12, s12, s17
	s_mulk_i32 s12, 0x1800
	v_lshl_add_u64 v[138:139], v[158:159], 0, s[12:13]
	s_add_i32 s12, s15, 4
	s_max_i32 s12, s12, s14
	s_min_i32 s12, s12, s17
	s_mulk_i32 s12, 0x1800
	v_lshl_add_u64 v[140:141], v[158:159], 0, s[12:13]
	s_add_i32 s12, s15, 5
	s_max_i32 s12, s12, s14
	s_min_i32 s12, s12, s17
	s_mulk_i32 s12, 0x1800
	v_lshl_add_u64 v[142:143], v[158:159], 0, s[12:13]
	s_add_i32 s12, s15, 6
	s_max_i32 s12, s12, s14
	s_min_i32 s12, s12, s17
	s_mulk_i32 s12, 0x1800
	v_lshl_add_u64 v[144:145], v[158:159], 0, s[12:13]
	s_add_i32 s12, s15, 7
	global_load_ushort v236, v[130:131], off
	global_load_ushort v233, v[132:133], off
	global_load_ushort v235, v[134:135], off
	global_load_ushort v232, v[136:137], off
	global_load_ushort v230, v[138:139], off
	global_load_ushort v229, v[140:141], off
	global_load_ushort v228, v[142:143], off
	global_load_ushort v227, v[144:145], off
	s_max_i32 s12, s12, s14
	s_min_i32 s12, s12, s17
	s_mulk_i32 s12, 0x1800
	s_add_i32 s15, s15, 8
	v_lshl_add_u64 v[130:131], v[158:159], 0, s[12:13]
	s_max_i32 s12, s15, s14
	s_min_i32 s12, s12, s17
	s_mulk_i32 s12, 0x1800
	v_lshl_add_u64 v[132:133], v[158:159], 0, s[12:13]
	global_load_ushort v234, v[130:131], off
	global_load_ushort v231, v[132:133], off
	s_waitcnt lgkmcnt(0)
	v_and_b32_e32 v168, 15, v1
	v_lshrrev_b32_e32 v169, 4, v1
	v_lshl_add_u32 v168, v168, 2, v169
	v_lshl_add_u32 v130, v168, 2, s18
	v_lshl_add_u32 v131, v1, 2, s18
	ds_read_b32 v132, v131 offset:0
	ds_read_b32 v135, v130 offset:768
	ds_read_b32 v133, v131 offset:256
	ds_read_b32 v134, v131 offset:512
	ds_read_b32 v136, v131 offset:1536
	ds_read_b32 v139, v130 offset:2304
	ds_read_b32 v137, v131 offset:1792
	ds_read_b32 v138, v131 offset:2048
	ds_read_b32 v140, v131 offset:3072
	ds_read_b32 v143, v130 offset:3840
	ds_read_b32 v141, v131 offset:3328
	ds_read_b32 v142, v131 offset:3584
	ds_read_b32 v144, v131 offset:4608
	ds_read_b32 v147, v130 offset:5376
	ds_read_b32 v145, v131 offset:4864
	ds_read_b32 v146, v131 offset:5120
	ds_read_b32 v148, v131 offset:6144
	ds_read_b32 v151, v130 offset:6912
	ds_read_b32 v149, v131 offset:6400
	ds_read_b32 v150, v131 offset:6656
	ds_read_b32 v152, v131 offset:7680
	ds_read_b32 v155, v130 offset:8448
	ds_read_b32 v153, v131 offset:7936
	ds_read_b32 v154, v131 offset:8192
	ds_read_b32 v156, v131 offset:9216
	ds_read_b32 v163, v130 offset:9984
	ds_read_b32 v157, v131 offset:9472
	ds_read_b32 v162, v131 offset:9728
	ds_read_b32 v164, v131 offset:10752
	ds_read_b32 v167, v130 offset:11520
	ds_read_b32 v165, v131 offset:11008
	ds_read_b32 v166, v131 offset:11264
	v_and_b32_e32 v248, 31, v1
	v_lshrrev_b32_e32 v249, 5, v1
	v_lshlrev_b32_e32 v160, 4, v249
	v_lshlrev_b32_e32 v250, 8, v249
	v_lshl_add_u32 v237, v248, 2, v250
	v_add_u32_e32 v237, 0x100, v237
	v_lshlrev_b32_e32 v251, 2, v248
	v_sub_u32_e32 v255, v251, v250
	v_add_u32_e32 v255, 0x200, v255
	s_mov_b32 s98, 0
	s_mov_b32 s99, -1
	s_waitcnt lgkmcnt(0)
	v_rcp_f32_e32 v239, v132
	v_mov_b32_e32 v238, v132
	s_nop 0
	v_mul_f32_e32 v133, v133, v239
	v_mul_f32_e32 v134, v134, v239
	ds_write_b32 v131, v135 offset:768
	ds_write_b32 v131, v133 offset:256
	ds_write_b32 v131, v134 offset:512
	v_mul_f32_e32 v139, v139, v238
	v_mul_f32_e32 v238, v238, v136
	v_rcp_f32_e32 v239, v238
	s_nop 0
	v_mul_f32_e32 v137, v137, v239
	v_mul_f32_e32 v138, v138, v239
	ds_write_b32 v131, v139 offset:2304
	ds_write_b32 v131, v137 offset:1792
	ds_write_b32 v131, v138 offset:2048
	v_mul_f32_e32 v143, v143, v238
	v_mul_f32_e32 v238, v238, v140
	v_rcp_f32_e32 v239, v238
	s_nop 0
	v_mul_f32_e32 v141, v141, v239
	v_mul_f32_e32 v142, v142, v239
	ds_write_b32 v131, v143 offset:3840
	ds_write_b32 v131, v141 offset:3328
	ds_write_b32 v131, v142 offset:3584
	v_mul_f32_e32 v147, v147, v238
	v_mul_f32_e32 v238, v238, v144
	v_rcp_f32_e32 v239, v238
	s_nop 0
	v_mul_f32_e32 v145, v145, v239
	v_mul_f32_e32 v146, v146, v239
	ds_write_b32 v131, v147 offset:5376
	ds_write_b32 v131, v145 offset:4864
	ds_write_b32 v131, v146 offset:5120
	v_mul_f32_e32 v151, v151, v238
	v_mul_f32_e32 v238, v238, v148
	v_rcp_f32_e32 v239, v238
	s_nop 0
	v_mul_f32_e32 v149, v149, v239
	v_mul_f32_e32 v150, v150, v239
	ds_write_b32 v131, v151 offset:6912
	ds_write_b32 v131, v149 offset:6400
	ds_write_b32 v131, v150 offset:6656
	v_mul_f32_e32 v155, v155, v238
	v_mul_f32_e32 v238, v238, v152
	v_rcp_f32_e32 v239, v238
	s_nop 0
	v_mul_f32_e32 v153, v153, v239
	v_mul_f32_e32 v154, v154, v239
	ds_write_b32 v131, v155 offset:8448
	ds_write_b32 v131, v153 offset:7936
	ds_write_b32 v131, v154 offset:8192
	v_mul_f32_e32 v163, v163, v238
	v_mul_f32_e32 v238, v238, v156
	v_rcp_f32_e32 v239, v238
	s_nop 0
	v_mul_f32_e32 v157, v157, v239
	v_mul_f32_e32 v162, v162, v239
	ds_write_b32 v131, v163 offset:9984
	ds_write_b32 v131, v157 offset:9472
	ds_write_b32 v131, v162 offset:9728
	v_mul_f32_e32 v167, v167, v238
	v_mul_f32_e32 v238, v238, v164
	v_rcp_f32_e32 v239, v238
	s_nop 0
	v_mul_f32_e32 v165, v165, v239
	v_mul_f32_e32 v166, v166, v239
	ds_write_b32 v131, v167 offset:11520
	ds_write_b32 v131, v165 offset:11008
	ds_write_b32 v131, v166 offset:11264
	ds_write_b32 v131, v238
	v_add_u32_e32 v253, s18, v160
	s_waitcnt lgkmcnt(0)
	ds_read_b128 v[130:133], v253 offset:768
	ds_read_b128 v[134:137], v253 offset:800
	ds_read_b128 v[138:141], v253 offset:832
	ds_read_b128 v[142:145], v253 offset:864
	ds_read_b128 v[146:149], v253 offset:896
	ds_read_b128 v[150:153], v253 offset:928
	ds_read_b128 v[154:157], v253 offset:960
	ds_read_b128 v[162:165], v253 offset:992
.LBB0_363:
	s_add_i32 s12, s18, s16
	v_add_u32_e32 v253, s12, v160
	v_add_u32_e32 v238, s12, v237
	v_add_u32_e32 v239, s12, v255
	v_xor_b32_e32 v240, 32, v1
	s_add_i32 s100, s12, 0x500
	v_lshl_add_u32 v240, v240, 2, s100
	ds_read_b32 v252, v240
	ds_read_b32 v248, v238
	ds_read_b32 v249, v238 offset:128
	ds_read_b32 v250, v239
	ds_read_b32 v251, v239 offset:128
	s_add_i32 s100, s12, 0x100
	v_lshl_add_u32 v241, v1, 2, s100
	ds_read_b32 v246, v241
	s_waitcnt lgkmcnt(13)
	v_pk_mul_f32 v[166:167], v[2:3], v[130:131]
	v_pk_mul_f32 v[168:169], v[34:35], v[130:131]
	v_pk_mul_f32 v[238:239], v[66:67], v[130:131]
	v_pk_mul_f32 v[240:241], v[98:99], v[130:131]
	v_pk_fma_f32 v[166:167], v[4:5], v[132:133], v[166:167]
	v_pk_fma_f32 v[168:169], v[36:37], v[132:133], v[168:169]
	v_pk_fma_f32 v[238:239], v[68:69], v[132:133], v[238:239]
	v_pk_fma_f32 v[240:241], v[100:101], v[132:133], v[240:241]
	s_waitcnt lgkmcnt(12)
	v_pk_fma_f32 v[166:167], v[6:7], v[134:135], v[166:167]
	v_pk_fma_f32 v[168:169], v[38:39], v[134:135], v[168:169]
	v_pk_fma_f32 v[238:239], v[70:71], v[134:135], v[238:239]
	v_pk_fma_f32 v[240:241], v[102:103], v[134:135], v[240:241]
	v_pk_fma_f32 v[166:167], v[8:9], v[136:137], v[166:167]
	v_pk_fma_f32 v[168:169], v[40:41], v[136:137], v[168:169]
	v_pk_fma_f32 v[238:239], v[72:73], v[136:137], v[238:239]
	v_pk_fma_f32 v[240:241], v[104:105], v[136:137], v[240:241]
	s_waitcnt lgkmcnt(11)
	v_pk_fma_f32 v[166:167], v[10:11], v[138:139], v[166:167]
	v_pk_fma_f32 v[168:169], v[42:43], v[138:139], v[168:169]
	v_pk_fma_f32 v[238:239], v[74:75], v[138:139], v[238:239]
	v_pk_fma_f32 v[240:241], v[106:107], v[138:139], v[240:241]
	v_pk_fma_f32 v[166:167], v[12:13], v[140:141], v[166:167]
	v_pk_fma_f32 v[168:169], v[44:45], v[140:141], v[168:169]
	v_pk_fma_f32 v[238:239], v[76:77], v[140:141], v[238:239]
	v_pk_fma_f32 v[240:241], v[108:109], v[140:141], v[240:241]
	s_waitcnt lgkmcnt(10)
	v_pk_fma_f32 v[166:167], v[14:15], v[142:143], v[166:167]
	v_pk_fma_f32 v[168:169], v[46:47], v[142:143], v[168:169]
	v_pk_fma_f32 v[238:239], v[78:79], v[142:143], v[238:239]
	v_pk_fma_f32 v[240:241], v[110:111], v[142:143], v[240:241]
	v_pk_fma_f32 v[166:167], v[16:17], v[144:145], v[166:167]
	v_pk_fma_f32 v[168:169], v[48:49], v[144:145], v[168:169]
	v_pk_fma_f32 v[238:239], v[80:81], v[144:145], v[238:239]
	v_pk_fma_f32 v[240:241], v[112:113], v[144:145], v[240:241]
	s_waitcnt lgkmcnt(9)
	v_pk_fma_f32 v[166:167], v[18:19], v[146:147], v[166:167]
	v_pk_fma_f32 v[168:169], v[50:51], v[146:147], v[168:169]
	v_pk_fma_f32 v[238:239], v[82:83], v[146:147], v[238:239]
	v_pk_fma_f32 v[240:241], v[114:115], v[146:147], v[240:241]
	v_pk_fma_f32 v[166:167], v[20:21], v[148:149], v[166:167]
	v_pk_fma_f32 v[168:169], v[52:53], v[148:149], v[168:169]
	v_pk_fma_f32 v[238:239], v[84:85], v[148:149], v[238:239]
	v_pk_fma_f32 v[240:241], v[116:117], v[148:149], v[240:241]
	s_waitcnt lgkmcnt(8)
	v_pk_fma_f32 v[166:167], v[22:23], v[150:151], v[166:167]
	v_pk_fma_f32 v[168:169], v[54:55], v[150:151], v[168:169]
	v_pk_fma_f32 v[238:239], v[86:87], v[150:151], v[238:239]
	v_pk_fma_f32 v[240:241], v[118:119], v[150:151], v[240:241]
	v_pk_fma_f32 v[166:167], v[24:25], v[152:153], v[166:167]
	v_pk_fma_f32 v[168:169], v[56:57], v[152:153], v[168:169]
	v_pk_fma_f32 v[238:239], v[88:89], v[152:153], v[238:239]
	v_pk_fma_f32 v[240:241], v[120:121], v[152:153], v[240:241]
	s_waitcnt lgkmcnt(7)
	v_pk_fma_f32 v[166:167], v[26:27], v[154:155], v[166:167]
	v_pk_fma_f32 v[168:169], v[58:59], v[154:155], v[168:169]
	v_pk_fma_f32 v[238:239], v[90:91], v[154:155], v[238:239]
	v_pk_fma_f32 v[240:241], v[122:123], v[154:155], v[240:241]
	v_pk_fma_f32 v[166:167], v[28:29], v[156:157], v[166:167]
	v_pk_fma_f32 v[168:169], v[60:61], v[156:157], v[168:169]
	v_pk_fma_f32 v[238:239], v[92:93], v[156:157], v[238:239]
	v_pk_fma_f32 v[240:241], v[124:125], v[156:157], v[240:241]
	s_waitcnt lgkmcnt(6)
	v_pk_fma_f32 v[166:167], v[30:31], v[162:163], v[166:167]
	v_pk_fma_f32 v[168:169], v[62:63], v[162:163], v[168:169]
	v_pk_fma_f32 v[238:239], v[94:95], v[162:163], v[238:239]
	v_pk_fma_f32 v[240:241], v[126:127], v[162:163], v[240:241]
	v_pk_fma_f32 v[166:167], v[32:33], v[164:165], v[166:167]
	v_pk_fma_f32 v[168:169], v[64:65], v[164:165], v[168:169]
	v_pk_fma_f32 v[238:239], v[96:97], v[164:165], v[238:239]
	v_pk_fma_f32 v[240:241], v[128:129], v[164:165], v[240:241]
	v_add_f32_e32 v244, v238, v239
	v_add_f32_e32 v245, v240, v241
	v_add_f32_e32 v242, v166, v167
	v_add_f32_e32 v243, v168, v169
	ds_read_b128 v[130:133], v253 offset:2304
	ds_read_b128 v[134:137], v253 offset:2336
	ds_read_b128 v[138:141], v253 offset:2368
	ds_read_b128 v[142:145], v253 offset:2400
	ds_read_b128 v[146:149], v253 offset:2432
	ds_read_b128 v[150:153], v253 offset:2464
	ds_read_b128 v[154:157], v253 offset:2496
	ds_read_b128 v[162:165], v253 offset:2528
	v_permlane32_swap_b32_e32 v244, v245
	v_permlane32_swap_b32_e32 v242, v243
	s_nop 0
	v_add_f32_e32 v247, v244, v245
	v_sub_f32_e64 v166, -v242, v243
	s_waitcnt lgkmcnt(8)
	v_cndmask_b32_e64 v168, -v247, v252, s[98:99]
	v_mov_b32_e32 v167, v166
	v_cndmask_b32_e64 v169, v252, -v247, s[98:99]
	s_nop 0
	v_permlane32_swap_b32_e32 v166, v167
	v_mfma_f32_32x32x2_f32 v[66:81], v248, v168, v[66:81]
	v_mfma_f32_32x32x2_f32 v[98:113], v250, v169, v[98:113]
	v_mfma_f32_32x32x1_2b_f32 v[2:33], v246, v166, v[2:33]
	v_mfma_f32_32x32x1_2b_f32 v[34:65], v246, v167, v[34:65]
	v_mfma_f32_32x32x2_f32 v[82:97], v249, v168, v[82:97]
	s_addk_i32 s16, 0x600
	s_cmpk_eq_i32 s16, 0x3000
	v_mfma_f32_32x32x2_f32 v[114:129], v251, v169, v[114:129]
	s_cbranch_scc0 .LBB0_363
	s_waitcnt lgkmcnt(0)
	v_add_u32_e32 v253, s18, v160
	ds_read_b128 v[130:133], v253 offset:0
	ds_read_b128 v[134:137], v253 offset:32
	ds_read_b128 v[138:141], v253 offset:64
	ds_read_b128 v[142:145], v253 offset:96
	ds_read_b128 v[146:149], v253 offset:128
	ds_read_b128 v[150:153], v253 offset:160
	ds_read_b128 v[154:157], v253 offset:192
	ds_read_b128 v[162:165], v253 offset:224
	s_nop 7
	s_nop 7
	s_waitcnt lgkmcnt(7)
	v_pk_mul_f32 v[66:67], v[66:67], v[130:131]
	v_pk_mul_f32 v[68:69], v[68:69], v[132:133]
	s_waitcnt lgkmcnt(6)
	v_pk_mul_f32 v[70:71], v[70:71], v[134:135]
	v_pk_mul_f32 v[72:73], v[72:73], v[136:137]
	s_waitcnt lgkmcnt(5)
	v_pk_mul_f32 v[74:75], v[74:75], v[138:139]
	v_pk_mul_f32 v[76:77], v[76:77], v[140:141]
	s_waitcnt lgkmcnt(4)
	v_pk_mul_f32 v[78:79], v[78:79], v[142:143]
	v_pk_mul_f32 v[80:81], v[80:81], v[144:145]
	s_waitcnt lgkmcnt(7)
	v_pk_mul_f32 v[98:99], v[98:99], v[130:131]
	v_pk_mul_f32 v[100:101], v[100:101], v[132:133]
	s_waitcnt lgkmcnt(6)
	v_pk_mul_f32 v[102:103], v[102:103], v[134:135]
	v_pk_mul_f32 v[104:105], v[104:105], v[136:137]
	s_waitcnt lgkmcnt(5)
	v_pk_mul_f32 v[106:107], v[106:107], v[138:139]
	v_pk_mul_f32 v[108:109], v[108:109], v[140:141]
	s_waitcnt lgkmcnt(4)
	v_pk_mul_f32 v[110:111], v[110:111], v[142:143]
	v_pk_mul_f32 v[112:113], v[112:113], v[144:145]
	s_waitcnt lgkmcnt(7)
	v_pk_mul_f32 v[2:3], v[2:3], v[130:131]
	v_pk_mul_f32 v[4:5], v[4:5], v[132:133]
	s_waitcnt lgkmcnt(6)
	v_pk_mul_f32 v[6:7], v[6:7], v[134:135]
	v_pk_mul_f32 v[8:9], v[8:9], v[136:137]
	s_waitcnt lgkmcnt(5)
	v_pk_mul_f32 v[10:11], v[10:11], v[138:139]
	v_pk_mul_f32 v[12:13], v[12:13], v[140:141]
	s_waitcnt lgkmcnt(4)
	v_pk_mul_f32 v[14:15], v[14:15], v[142:143]
	v_pk_mul_f32 v[16:17], v[16:17], v[144:145]
	s_waitcnt lgkmcnt(7)
	v_pk_mul_f32 v[34:35], v[34:35], v[130:131]
	v_pk_mul_f32 v[36:37], v[36:37], v[132:133]
	s_waitcnt lgkmcnt(6)
	v_pk_mul_f32 v[38:39], v[38:39], v[134:135]
	v_pk_mul_f32 v[40:41], v[40:41], v[136:137]
	s_waitcnt lgkmcnt(5)
	v_pk_mul_f32 v[42:43], v[42:43], v[138:139]
	v_pk_mul_f32 v[44:45], v[44:45], v[140:141]
	s_waitcnt lgkmcnt(4)
	v_pk_mul_f32 v[46:47], v[46:47], v[142:143]
	v_pk_mul_f32 v[48:49], v[48:49], v[144:145]
	s_waitcnt lgkmcnt(3)
	v_pk_mul_f32 v[18:19], v[18:19], v[146:147]
	v_pk_mul_f32 v[20:21], v[20:21], v[148:149]
	s_waitcnt lgkmcnt(2)
	v_pk_mul_f32 v[22:23], v[22:23], v[150:151]
	v_pk_mul_f32 v[24:25], v[24:25], v[152:153]
	s_waitcnt lgkmcnt(1)
	v_pk_mul_f32 v[26:27], v[26:27], v[154:155]
	v_pk_mul_f32 v[28:29], v[28:29], v[156:157]
	s_waitcnt lgkmcnt(0)
	v_pk_mul_f32 v[30:31], v[30:31], v[162:163]
	v_pk_mul_f32 v[32:33], v[32:33], v[164:165]
	s_waitcnt lgkmcnt(3)
	v_pk_mul_f32 v[50:51], v[50:51], v[146:147]
	v_pk_mul_f32 v[52:53], v[52:53], v[148:149]
	s_waitcnt lgkmcnt(2)
	v_pk_mul_f32 v[54:55], v[54:55], v[150:151]
	v_pk_mul_f32 v[56:57], v[56:57], v[152:153]
	s_waitcnt lgkmcnt(1)
	v_pk_mul_f32 v[58:59], v[58:59], v[154:155]
	v_pk_mul_f32 v[60:61], v[60:61], v[156:157]
	s_waitcnt lgkmcnt(0)
	v_pk_mul_f32 v[62:63], v[62:63], v[162:163]
	v_pk_mul_f32 v[64:65], v[64:65], v[164:165]
	s_waitcnt lgkmcnt(3)
	v_pk_mul_f32 v[82:83], v[82:83], v[146:147]
	v_pk_mul_f32 v[84:85], v[84:85], v[148:149]
	s_waitcnt lgkmcnt(2)
	v_pk_mul_f32 v[86:87], v[86:87], v[150:151]
	v_pk_mul_f32 v[88:89], v[88:89], v[152:153]
	s_waitcnt lgkmcnt(1)
	v_pk_mul_f32 v[90:91], v[90:91], v[154:155]
	v_pk_mul_f32 v[92:93], v[92:93], v[156:157]
	s_waitcnt lgkmcnt(0)
	v_pk_mul_f32 v[94:95], v[94:95], v[162:163]
	v_pk_mul_f32 v[96:97], v[96:97], v[164:165]
	s_waitcnt lgkmcnt(3)
	v_pk_mul_f32 v[114:115], v[114:115], v[146:147]
	v_pk_mul_f32 v[116:117], v[116:117], v[148:149]
	s_waitcnt lgkmcnt(2)
	v_pk_mul_f32 v[118:119], v[118:119], v[150:151]
	v_pk_mul_f32 v[120:121], v[120:121], v[152:153]
	s_waitcnt lgkmcnt(1)
	v_pk_mul_f32 v[122:123], v[122:123], v[154:155]
	v_pk_mul_f32 v[124:125], v[124:125], v[156:157]
	s_waitcnt lgkmcnt(0)
	v_pk_mul_f32 v[126:127], v[126:127], v[162:163]
	v_pk_mul_f32 v[128:129], v[128:129], v[164:165]
	s_cmp_eq_u32 s20, 26
	s_cbranch_scc0 .LBB0_335
	s_ashr_i32 s1, s0, 31
	s_lshl_b64 s[0:1], s[0:1], 15
	s_add_u32 s0, s88, s0
	s_addc_u32 s1, s89, s1
	v_and_b32_e32 v130, 31, v1
	v_lshrrev_b32_e32 v131, 5, v1
	v_lshlrev_b32_e32 v130, 8, v130
	v_lshl_add_u32 v130, v131, 4, v130
	v_mov_b32_e32 v131, 0
	v_lshl_add_u64 v[130:131], s[0:1], 0, v[130:131]
	s_mov_b64 s[0:1], 0x6180000
	v_lshl_add_u64 v[130:131], v[130:131], 0, s[0:1]
	s_mov_b64 s[0:1], 0x2000
	v_lshl_add_u64 v[132:133], v[130:131], 0, s[0:1]
	v_lshl_add_u64 v[136:137], v[132:133], 0, s[0:1]
	v_lshl_add_u64 v[138:139], v[136:137], 0, s[0:1]
	s_nop 8
	s_nop 8
	global_store_dwordx4 v[130:131], v[2:5], off
	global_store_dwordx4 v[130:131], v[6:9], off offset:32
	global_store_dwordx4 v[130:131], v[10:13], off offset:64
	global_store_dwordx4 v[130:131], v[14:17], off offset:96
	global_store_dwordx4 v[130:131], v[18:21], off offset:128
	global_store_dwordx4 v[130:131], v[22:25], off offset:160
	global_store_dwordx4 v[130:131], v[26:29], off offset:192
	global_store_dwordx4 v[130:131], v[30:33], off offset:224
	global_store_dwordx4 v[132:133], v[34:37], off
	global_store_dwordx4 v[132:133], v[38:41], off offset:32
	global_store_dwordx4 v[132:133], v[42:45], off offset:64
	global_store_dwordx4 v[132:133], v[46:49], off offset:96
	global_store_dwordx4 v[132:133], v[50:53], off offset:128
	global_store_dwordx4 v[132:133], v[54:57], off offset:160
	global_store_dwordx4 v[132:133], v[58:61], off offset:192
	global_store_dwordx4 v[132:133], v[62:65], off offset:224
	global_store_dwordx4 v[136:137], v[66:69], off
	global_store_dwordx4 v[136:137], v[70:73], off offset:32
	global_store_dwordx4 v[136:137], v[74:77], off offset:64
	global_store_dwordx4 v[136:137], v[78:81], off offset:96
	global_store_dwordx4 v[136:137], v[82:85], off offset:128
	global_store_dwordx4 v[136:137], v[86:89], off offset:160
	global_store_dwordx4 v[136:137], v[90:93], off offset:192
	global_store_dwordx4 v[136:137], v[94:97], off offset:224
	global_store_dwordx4 v[138:139], v[98:101], off
	global_store_dwordx4 v[138:139], v[102:105], off offset:32
	global_store_dwordx4 v[138:139], v[106:109], off offset:64
	global_store_dwordx4 v[138:139], v[110:113], off offset:96
	global_store_dwordx4 v[138:139], v[114:117], off offset:128
	global_store_dwordx4 v[138:139], v[118:121], off offset:160
	global_store_dwordx4 v[138:139], v[122:125], off offset:192
	global_store_dwordx4 v[138:139], v[126:129], off offset:224

.LBB0_728:
	s_or_b64 exec, exec, s[8:9]
	s_setprio 0
	s_waitcnt lgkmcnt(0)
	v_and_b32_e32 v108, 15, v1
	v_lshrrev_b32_e32 v109, 4, v1
	v_lshl_add_u32 v108, v108, 2, v109
	v_lshl_add_u32 v66, v108, 2, s30
	v_lshl_add_u32 v67, v1, 2, s30
	ds_read_b32 v68, v67 offset:0
	ds_read_b32 v71, v66 offset:768
	ds_read_b32 v69, v67 offset:256
	ds_read_b32 v70, v67 offset:512
	ds_read_b32 v72, v66 offset:1024
	ds_read_b32 v73, v67 offset:1536
	ds_read_b32 v76, v66 offset:2304
	ds_read_b32 v74, v67 offset:1792
	ds_read_b32 v75, v67 offset:2048
	ds_read_b32 v77, v66 offset:2560
	ds_read_b32 v78, v67 offset:3072
	ds_read_b32 v81, v66 offset:3840
	ds_read_b32 v79, v67 offset:3328
	ds_read_b32 v80, v67 offset:3584
	ds_read_b32 v82, v66 offset:4096
	ds_read_b32 v83, v67 offset:4608
	ds_read_b32 v86, v66 offset:5376
	ds_read_b32 v84, v67 offset:4864
	ds_read_b32 v85, v67 offset:5120
	ds_read_b32 v87, v66 offset:5632
	ds_read_b32 v88, v67 offset:6144
	ds_read_b32 v91, v66 offset:6912
	ds_read_b32 v89, v67 offset:6400
	ds_read_b32 v90, v67 offset:6656
	ds_read_b32 v92, v66 offset:7168
	ds_read_b32 v93, v67 offset:7680
	ds_read_b32 v96, v66 offset:8448
	ds_read_b32 v94, v67 offset:7936
	ds_read_b32 v95, v67 offset:8192
	ds_read_b32 v97, v66 offset:8704
	ds_read_b32 v98, v67 offset:9216
	ds_read_b32 v101, v66 offset:9984
	ds_read_b32 v99, v67 offset:9472
	ds_read_b32 v100, v67 offset:9728
	ds_read_b32 v102, v66 offset:10240
	ds_read_b32 v103, v67 offset:10752
	ds_read_b32 v106, v66 offset:11520
	ds_read_b32 v104, v67 offset:11008
	ds_read_b32 v105, v67 offset:11264
	ds_read_b32 v107, v66 offset:11776
	v_and_b32_e32 v118, 31, v1
	v_lshrrev_b32_e32 v119, 5, v1
	v_lshlrev_b32_e32 v240, 4, v119
	v_lshlrev_b32_e32 v120, 8, v119
	v_lshl_add_u32 v241, v118, 2, v120
	v_add_u32_e32 v241, 0x100, v241
	v_lshlrev_b32_e32 v121, 2, v118
	v_sub_u32_e32 v242, v121, v120
	v_add_u32_e32 v242, 0x200, v242
	v_xor_b32_e32 v121, 32, v1
	v_lshlrev_b32_e32 v121, 2, v121
	v_add_u32_e32 v243, 0x500, v121
	s_mov_b32 s98, 0
	s_mov_b32 s99, -1
	s_waitcnt lgkmcnt(0)
	v_rcp_f32_e32 v111, v68
	v_mov_b32_e32 v110, v68
	v_mul_f32_e32 v72, v72, v110
	v_mul_f32_e32 v69, v69, v111
	v_mul_f32_e32 v70, v70, v111
	ds_write_b32 v67, v71 offset:768
	ds_write_b32 v67, v72 offset:1024
	ds_write_b32 v67, v69 offset:256
	ds_write_b32 v67, v70 offset:512
	v_mul_f32_e32 v76, v76, v110
	v_mul_f32_e32 v110, v110, v73
	v_rcp_f32_e32 v111, v110
	v_mul_f32_e32 v77, v77, v110
	v_mul_f32_e32 v74, v74, v111
	v_mul_f32_e32 v75, v75, v111
	ds_write_b32 v67, v76 offset:2304
	ds_write_b32 v67, v77 offset:2560
	ds_write_b32 v67, v74 offset:1792
	ds_write_b32 v67, v75 offset:2048
	v_mul_f32_e32 v81, v81, v110
	v_mul_f32_e32 v110, v110, v78
	v_rcp_f32_e32 v111, v110
	v_mul_f32_e32 v82, v82, v110
	v_mul_f32_e32 v79, v79, v111
	v_mul_f32_e32 v80, v80, v111
	ds_write_b32 v67, v81 offset:3840
	ds_write_b32 v67, v82 offset:4096
	ds_write_b32 v67, v79 offset:3328
	ds_write_b32 v67, v80 offset:3584
	v_mul_f32_e32 v86, v86, v110
	v_mul_f32_e32 v110, v110, v83
	v_rcp_f32_e32 v111, v110
	v_mul_f32_e32 v87, v87, v110
	v_mul_f32_e32 v84, v84, v111
	v_mul_f32_e32 v85, v85, v111
	ds_write_b32 v67, v86 offset:5376
	ds_write_b32 v67, v87 offset:5632
	ds_write_b32 v67, v84 offset:4864
	ds_write_b32 v67, v85 offset:5120
	v_mul_f32_e32 v91, v91, v110
	v_mul_f32_e32 v110, v110, v88
	v_rcp_f32_e32 v111, v110
	v_mul_f32_e32 v92, v92, v110
	v_mul_f32_e32 v89, v89, v111
	v_mul_f32_e32 v90, v90, v111
	ds_write_b32 v67, v91 offset:6912
	ds_write_b32 v67, v92 offset:7168
	ds_write_b32 v67, v89 offset:6400
	ds_write_b32 v67, v90 offset:6656
	v_mul_f32_e32 v96, v96, v110
	v_mul_f32_e32 v110, v110, v93
	v_rcp_f32_e32 v111, v110
	v_mul_f32_e32 v97, v97, v110
	v_mul_f32_e32 v94, v94, v111
	v_mul_f32_e32 v95, v95, v111
	ds_write_b32 v67, v96 offset:8448
	ds_write_b32 v67, v97 offset:8704
	ds_write_b32 v67, v94 offset:7936
	ds_write_b32 v67, v95 offset:8192
	v_mul_f32_e32 v101, v101, v110
	v_mul_f32_e32 v110, v110, v98
	v_rcp_f32_e32 v111, v110
	v_mul_f32_e32 v102, v102, v110
	v_mul_f32_e32 v99, v99, v111
	v_mul_f32_e32 v100, v100, v111
	ds_write_b32 v67, v101 offset:9984
	ds_write_b32 v67, v102 offset:10240
	ds_write_b32 v67, v99 offset:9472
	ds_write_b32 v67, v100 offset:9728
	v_mul_f32_e32 v106, v106, v110
	v_mul_f32_e32 v110, v110, v103
	v_rcp_f32_e32 v111, v110
	v_mul_f32_e32 v107, v107, v110
	v_mul_f32_e32 v104, v104, v111
	v_mul_f32_e32 v105, v105, v111
	ds_write_b32 v67, v106 offset:11520
	ds_write_b32 v67, v107 offset:11776
	ds_write_b32 v67, v104 offset:11008
	ds_write_b32 v67, v105 offset:11264
	ds_write_b32 v67, v110
	v_add_u32_e32 v229, s30, v240
	s_waitcnt lgkmcnt(0)
	ds_read_b128 v[66:69], v229 offset:768
	ds_read_b128 v[70:73], v229 offset:800
	ds_read_b128 v[74:77], v229 offset:832
	ds_read_b128 v[78:81], v229 offset:864
	ds_read_b128 v[82:85], v229 offset:896
	ds_read_b128 v[86:89], v229 offset:928
	ds_read_b128 v[90:93], v229 offset:960
	ds_read_b128 v[94:97], v229 offset:992
	s_mov_b32 s8, 8
	s_mov_b32 s9, s30
	s_mov_b32 s18, s12
.LBB0_729:
	v_add_u32_e32 v229, s9, v240
	v_add_u32_e32 v232, s9, v243
	v_add_u32_e32 v230, s9, v241
	v_add_u32_e32 v231, s9, v242
	v_mov_b32_e32 v233, s18
	ds_read_b32 v224, v232
	ds_read_b32 v225, v233
	ds_read_b32 v150, v230
	ds_read_b32 v152, v230 offset:128
	ds_read_b32 v153, v231
	ds_read_b32 v154, v231 offset:128
	s_waitcnt lgkmcnt(13)
	v_pk_mul_f32 v[130:131], v[2:3], v[66:67]
	v_pk_mul_f32 v[132:133], v[4:5], v[68:69]
	v_pk_mul_f32 v[134:135], v[34:35], v[66:67]
	v_pk_mul_f32 v[136:137], v[36:37], v[68:69]
	ds_read_b128 v[98:101], v229 offset:1024
	s_waitcnt lgkmcnt(13)
	v_pk_fma_f32 v[130:131], v[6:7], v[70:71], v[130:131]
	v_pk_fma_f32 v[132:133], v[8:9], v[72:73], v[132:133]
	v_pk_fma_f32 v[134:135], v[38:39], v[70:71], v[134:135]
	v_pk_fma_f32 v[136:137], v[40:41], v[72:73], v[136:137]
	ds_read_b128 v[102:105], v229 offset:1056
	s_waitcnt lgkmcnt(13)
	v_pk_fma_f32 v[130:131], v[10:11], v[74:75], v[130:131]
	v_pk_fma_f32 v[132:133], v[12:13], v[76:77], v[132:133]
	v_pk_fma_f32 v[134:135], v[42:43], v[74:75], v[134:135]
	v_pk_fma_f32 v[136:137], v[44:45], v[76:77], v[136:137]
	ds_read_b128 v[106:109], v229 offset:1088
	s_waitcnt lgkmcnt(13)
	v_pk_fma_f32 v[130:131], v[14:15], v[78:79], v[130:131]
	v_pk_fma_f32 v[132:133], v[16:17], v[80:81], v[132:133]
	v_pk_fma_f32 v[134:135], v[46:47], v[78:79], v[134:135]
	v_pk_fma_f32 v[136:137], v[48:49], v[80:81], v[136:137]
	ds_read_b128 v[110:113], v229 offset:1120
	s_waitcnt lgkmcnt(13)
	v_pk_fma_f32 v[130:131], v[18:19], v[82:83], v[130:131]
	v_pk_fma_f32 v[132:133], v[20:21], v[84:85], v[132:133]
	v_pk_fma_f32 v[134:135], v[50:51], v[82:83], v[134:135]
	v_pk_fma_f32 v[136:137], v[52:53], v[84:85], v[136:137]
	ds_read_b128 v[114:117], v229 offset:1152
	s_waitcnt lgkmcnt(13)
	v_pk_fma_f32 v[130:131], v[22:23], v[86:87], v[130:131]
	v_pk_fma_f32 v[132:133], v[24:25], v[88:89], v[132:133]
	v_pk_fma_f32 v[134:135], v[54:55], v[86:87], v[134:135]
	v_pk_fma_f32 v[136:137], v[56:57], v[88:89], v[136:137]
	ds_read_b128 v[118:121], v229 offset:1184
	s_waitcnt lgkmcnt(13)
	v_pk_fma_f32 v[130:131], v[26:27], v[90:91], v[130:131]
	v_pk_fma_f32 v[132:133], v[28:29], v[92:93], v[132:133]
	v_pk_fma_f32 v[134:135], v[58:59], v[90:91], v[134:135]
	v_pk_fma_f32 v[136:137], v[60:61], v[92:93], v[136:137]
	ds_read_b128 v[122:125], v229 offset:1216
	s_waitcnt lgkmcnt(13)
	v_pk_fma_f32 v[130:131], v[30:31], v[94:95], v[130:131]
	v_pk_fma_f32 v[132:133], v[32:33], v[96:97], v[132:133]
	v_pk_fma_f32 v[134:135], v[62:63], v[94:95], v[134:135]
	v_pk_fma_f32 v[136:137], v[64:65], v[96:97], v[136:137]
	ds_read_b128 v[126:129], v229 offset:1248
	v_pk_add_f32 v[130:131], v[130:131], v[132:133]
	v_pk_add_f32 v[134:135], v[134:135], v[136:137]
	v_add_f32_e32 v226, v130, v131
	v_add_f32_e32 v227, v134, v135
	ds_read_b128 v[66:69], v229 offset:2304
	ds_read_b128 v[70:73], v229 offset:2336
	ds_read_b128 v[74:77], v229 offset:2368
	ds_read_b128 v[78:81], v229 offset:2400
	ds_read_b128 v[82:85], v229 offset:2432
	ds_read_b128 v[86:89], v229 offset:2464
	ds_read_b128 v[90:93], v229 offset:2496
	ds_read_b128 v[94:97], v229 offset:2528
	v_permlane32_swap_b32_e32 v226, v227
	s_nop 0
	v_add_f32_e32 v228, v226, v227
	s_waitcnt lgkmcnt(14)
	v_cndmask_b32_e64 v155, -v228, v224, s[98:99]
	v_cndmask_b32_e64 v223, v224, -v228, s[98:99]
	s_nop 1
	v_mfma_f32_32x32x2_f32 v[2:17], v150, v155, v[2:17]
	v_mfma_f32_32x32x2_f32 v[34:49], v153, v223, v[34:49]
	v_mfma_f32_32x32x2_f32 v[18:33], v152, v155, v[18:33]
	v_mfma_f32_32x32x2_f32 v[50:65], v154, v223, v[50:65]
	s_add_i32 s8, s8, -1
	s_addk_i32 s18, 0x90
	s_nop 7
	s_nop 7
	s_waitcnt lgkmcnt(14)
	v_pk_mul_f32 v[138:139], v[2:3], v[98:99]
	v_pk_mul_f32 v[140:141], v[4:5], v[100:101]
	s_waitcnt lgkmcnt(14)
	v_pk_fma_f32 v[138:139], v[6:7], v[102:103], v[138:139]
	v_pk_fma_f32 v[140:141], v[8:9], v[104:105], v[140:141]
	s_waitcnt lgkmcnt(13)
	v_pk_fma_f32 v[138:139], v[10:11], v[106:107], v[138:139]
	v_pk_fma_f32 v[140:141], v[12:13], v[108:109], v[140:141]
	s_waitcnt lgkmcnt(12)
	v_pk_fma_f32 v[138:139], v[14:15], v[110:111], v[138:139]
	v_pk_fma_f32 v[140:141], v[16:17], v[112:113], v[140:141]
	s_waitcnt lgkmcnt(14)
	v_pk_mul_f32 v[142:143], v[34:35], v[98:99]
	v_pk_mul_f32 v[144:145], v[36:37], v[100:101]
	s_waitcnt lgkmcnt(14)
	v_pk_fma_f32 v[142:143], v[38:39], v[102:103], v[142:143]
	v_pk_fma_f32 v[144:145], v[40:41], v[104:105], v[144:145]
	s_waitcnt lgkmcnt(13)
	v_pk_fma_f32 v[142:143], v[42:43], v[106:107], v[142:143]
	v_pk_fma_f32 v[144:145], v[44:45], v[108:109], v[144:145]
	s_waitcnt lgkmcnt(12)
	v_pk_fma_f32 v[142:143], v[46:47], v[110:111], v[142:143]
	v_pk_fma_f32 v[144:145], v[48:49], v[112:113], v[144:145]
	s_waitcnt lgkmcnt(11)
	v_pk_fma_f32 v[138:139], v[18:19], v[114:115], v[138:139]
	v_pk_fma_f32 v[140:141], v[20:21], v[116:117], v[140:141]
	s_waitcnt lgkmcnt(10)
	v_pk_fma_f32 v[138:139], v[22:23], v[118:119], v[138:139]
	v_pk_fma_f32 v[140:141], v[24:25], v[120:121], v[140:141]
	s_waitcnt lgkmcnt(9)
	v_pk_fma_f32 v[138:139], v[26:27], v[122:123], v[138:139]
	v_pk_fma_f32 v[140:141], v[28:29], v[124:125], v[140:141]
	s_waitcnt lgkmcnt(8)
	v_pk_fma_f32 v[138:139], v[30:31], v[126:127], v[138:139]
	v_pk_fma_f32 v[140:141], v[32:33], v[128:129], v[140:141]
	s_waitcnt lgkmcnt(11)
	v_pk_fma_f32 v[142:143], v[50:51], v[114:115], v[142:143]
	v_pk_fma_f32 v[144:145], v[52:53], v[116:117], v[144:145]
	s_waitcnt lgkmcnt(10)
	v_pk_fma_f32 v[142:143], v[54:55], v[118:119], v[142:143]
	v_pk_fma_f32 v[144:145], v[56:57], v[120:121], v[144:145]
	s_waitcnt lgkmcnt(9)
	v_pk_fma_f32 v[142:143], v[58:59], v[122:123], v[142:143]
	v_pk_fma_f32 v[144:145], v[60:61], v[124:125], v[144:145]
	s_waitcnt lgkmcnt(8)
	v_pk_fma_f32 v[142:143], v[62:63], v[126:127], v[142:143]
	v_pk_fma_f32 v[144:145], v[64:65], v[128:129], v[144:145]
	v_pk_add_f32 v[138:139], v[138:139], v[140:141]
	v_pk_add_f32 v[142:143], v[142:143], v[144:145]
	v_add_f32_e32 v226, v138, v139
	v_add_f32_e32 v227, v142, v143
	s_addk_i32 s9, 0x600
	s_nop 0
	v_permlane32_swap_b32_e32 v226, v227
	s_nop 0
	v_add_f32_e32 v228, v226, v227
	v_bfe_u32 v234, v228, 16, 1
	v_add3_u32 v235, v228, v234, s35
	v_mad_i64_i32 v[236:237], s[20:21], v225, s31, v[146:147]
	s_cmp_eq_u32 s8, 0
	global_store_short_d16_hi v[236:237], v235, off
	s_cbranch_scc0 .LBB0_729
	s_waitcnt lgkmcnt(0)
	v_add_u32_e32 v229, s30, v240
	ds_read_b128 v[66:69], v229 offset:0
	ds_read_b128 v[70:73], v229 offset:32
	ds_read_b128 v[74:77], v229 offset:64
	ds_read_b128 v[78:81], v229 offset:96
	ds_read_b128 v[82:85], v229 offset:128
	ds_read_b128 v[86:89], v229 offset:160
	ds_read_b128 v[90:93], v229 offset:192
	ds_read_b128 v[94:97], v229 offset:224
	s_waitcnt lgkmcnt(7)
	v_pk_mul_f32 v[2:3], v[2:3], v[66:67]
	v_pk_mul_f32 v[4:5], v[4:5], v[68:69]
	s_waitcnt lgkmcnt(6)
	v_pk_mul_f32 v[6:7], v[6:7], v[70:71]
	v_pk_mul_f32 v[8:9], v[8:9], v[72:73]
	s_waitcnt lgkmcnt(5)
	v_pk_mul_f32 v[10:11], v[10:11], v[74:75]
	v_pk_mul_f32 v[12:13], v[12:13], v[76:77]
	s_waitcnt lgkmcnt(4)
	v_pk_mul_f32 v[14:15], v[14:15], v[78:79]
	v_pk_mul_f32 v[16:17], v[16:17], v[80:81]
	v_pk_mul_f32 v[34:35], v[34:35], v[66:67]
	v_pk_mul_f32 v[36:37], v[36:37], v[68:69]
	v_pk_mul_f32 v[38:39], v[38:39], v[70:71]
	v_pk_mul_f32 v[40:41], v[40:41], v[72:73]
	v_pk_mul_f32 v[42:43], v[42:43], v[74:75]
	v_pk_mul_f32 v[44:45], v[44:45], v[76:77]
	v_pk_mul_f32 v[46:47], v[46:47], v[78:79]
	v_pk_mul_f32 v[48:49], v[48:49], v[80:81]
	s_waitcnt lgkmcnt(3)
	v_pk_mul_f32 v[18:19], v[18:19], v[82:83]
	v_pk_mul_f32 v[20:21], v[20:21], v[84:85]
	s_waitcnt lgkmcnt(2)
	v_pk_mul_f32 v[22:23], v[22:23], v[86:87]
	v_pk_mul_f32 v[24:25], v[24:25], v[88:89]
	s_waitcnt lgkmcnt(1)
	v_pk_mul_f32 v[26:27], v[26:27], v[90:91]
	v_pk_mul_f32 v[28:29], v[28:29], v[92:93]
	s_waitcnt lgkmcnt(0)
	v_pk_mul_f32 v[30:31], v[30:31], v[94:95]
	v_pk_mul_f32 v[32:33], v[32:33], v[96:97]
	v_pk_mul_f32 v[50:51], v[50:51], v[82:83]
	v_pk_mul_f32 v[52:53], v[52:53], v[84:85]
	v_pk_mul_f32 v[54:55], v[54:55], v[86:87]
	v_pk_mul_f32 v[56:57], v[56:57], v[88:89]
	v_pk_mul_f32 v[58:59], v[58:59], v[90:91]
	v_pk_mul_f32 v[60:61], v[60:61], v[92:93]
	v_pk_mul_f32 v[62:63], v[62:63], v[94:95]
	v_pk_mul_f32 v[64:65], v[64:65], v[96:97]
	s_add_i32 s13, s13, 1
	s_cmp_eq_u32 s13, 26
	s_cbranch_scc0 .LBB0_701
